# gating mixer: u-tile loads hoisted to the top of each quarter (as previous version) + item preamble issues the second half of the row statistics and the bias loads together with the first half (one me
# baseline (speedup 1.0000x reference)
; #define lane (hw_lane())
; __device__ __forceinline__ void sgu_item(LAS unsigned char* wl, const bf16* proj, bf16* ymix, const float* vstat, const float* sgu_g, const bf16* Wm, const float* sgu_b, int chunk, int h, int lane) {
;     ...
;     for (int hh = 0; hh < 2; ++hh) { const f32x4* sp = (const f32x4*)(vstat + (R0 + lane + 64 * hh) * 16);
;         const f32x4 a = sp[0], b = sp[1], c = sp[2], d = sp[3];
;         const float s1 = ((a[0] + a[2]) + (b[0] + b[2])) + ((c[0] + c[2]) + (d[0] + d[2])), s2 = ((a[1] + a[3]) + (b[1] + b[3])) + ((c[1] + c[3]) + (d[1] + d[3]));
;         const float mean = s1 * (1.0f / 512.0f), var = fmaxf(s2 * (1.0f / 512.0f) - mean * mean, 0.f);
;         st[lane + 64 * hh] = (f32x2){mean, __builtin_amdgcn_rsqf(var + EPS)}; }
;     bf16x8 wmf[20];
;     { const bf16* wm = Wm + (size_t)(h * 128 + r) * 128 + q * 8; int f = 0;
; #pragma unroll
;       for (int ks = 0; ks < 4; ++ks)
; #pragma unroll
;         for (int tb = 2 * ks; tb < 8; ++tb) wmf[f++] = *(const bf16x8*)(wm + (size_t)(16 * tb) * 128 + ks * 32); }
;     float bias[8];
; #pragma unroll
;     for (int tb = 0; tb < 8; ++tb) bias[tb] = sgu_b[h * 128 + 16 * tb + r];
.LBB0_510:
	s_ashr_i32 s0, s5, 2
	s_ashr_i32 s1, s0, 31
	s_lshl_b64 s[8:9], s[0:1], 7
	v_mov_b32_e32 v1, s9
	v_or_b32_e32 v0, s8, v140
	v_lshlrev_b64 v[0:1], 6, v[0:1]
	v_lshl_add_u64 v[12:13], s[18:19], 0, v[0:1]
	global_load_dwordx4 v[0:3], v[12:13], off
	global_load_dwordx4 v[4:7], v[12:13], off offset:16
	global_load_dwordx4 v[8:11], v[12:13], off offset:32
	s_nop 0
	global_load_dwordx4 v[12:15], v[12:13], off offset:48
	s_mov_b32 s10, 0x3b000000
	v_mov_b32_e32 v17, s9
	v_or_b32_e32 v16, s8, v142
	s_lshl_b32 s6, s5, 7
	s_and_b32 s6, s6, 0x180
	s_lshl_b64 s[8:9], s[0:1], 18
	s_mov_b64 s[20:21], 0
	v_lshlrev_b64 v[20:21], 6, v[16:17]
	v_or_b32_e32 v22, s6, v143
	v_lshl_add_u64 v[20:21], s[18:19], 0, v[20:21]
	v_lshlrev_b32_e32 v22, 2, v22
	global_load_dwordx4 v[24:27], v[20:21], off
	global_load_dwordx4 v[28:31], v[20:21], off offset:16
	global_load_dwordx4 v[32:35], v[20:21], off offset:32
	global_load_dwordx4 v[36:39], v[20:21], off offset:48
	global_load_dword v162, v22, s[14:15]
	global_load_dword v164, v22, s[14:15] offset:64
	global_load_dword v166, v22, s[14:15] offset:128
	global_load_dword v168, v22, s[14:15] offset:192
	global_load_dword v170, v22, s[14:15] offset:256
	global_load_dword v172, v22, s[14:15] offset:320
	global_load_dword v174, v22, s[14:15] offset:384
	global_load_dword v176, v22, s[14:15] offset:448
	s_waitcnt vmcnt(12) lgkmcnt(0)
	v_pk_add_f32 v[0:1], v[0:1], v[2:3]
	v_pk_add_f32 v[2:3], v[4:5], v[6:7]
	v_pk_add_f32 v[4:5], v[8:9], v[10:11]
	v_pk_add_f32 v[6:7], v[12:13], v[14:15]
	v_pk_add_f32 v[0:1], v[0:1], v[2:3]
	v_pk_add_f32 v[2:3], v[4:5], v[6:7]
	s_nop 0
	v_pk_add_f32 v[0:1], v[0:1], v[2:3]
	v_lshlrev_b64 v[2:3], 6, v[16:17]
	v_pk_mul_f32 v[0:1], v[0:1], s[10:11] op_sel_hi:[1,0]
	v_lshl_add_u64 v[12:13], s[18:19], 0, v[2:3]
	v_fma_f32 v1, -v0, v0, v1
	v_max_f32_e32 v1, 0, v1
	v_add_f32_e32 v1, 0x358637bd, v1
	v_rsq_f32_e32 v1, v1
	v_or_b32_e32 v16, s6, v143
	v_lshlrev_b32_e32 v192, 8, v16
	v_lshlrev_b32_e32 v18, 2, v16
	ds_write_b64 v141, v[0:1] offset:10240
	v_lshl_add_u64 v[16:17], v[144:145], 0, v[192:193]
	s_movk_i32 s6, 0x1000
	v_add_co_u32_e32 v18, vcc, s6, v16
	s_movk_i32 s6, 0x2000
	s_nop 0
	v_addc_co_u32_e32 v19, vcc, 0, v17, vcc
	v_add_co_u32_e32 v20, vcc, s6, v16
	s_movk_i32 s6, 0x3000
	s_nop 0
	v_addc_co_u32_e32 v21, vcc, 0, v17, vcc
	v_add_co_u32_e32 v22, vcc, s6, v16
	s_movk_i32 s6, 0x4000
	s_nop 0
	v_addc_co_u32_e32 v23, vcc, 0, v17, vcc
	v_add_co_u32_e32 v52, vcc, s6, v16
	s_movk_i32 s6, 0x5000
	s_nop 0
	v_addc_co_u32_e32 v53, vcc, 0, v17, vcc
	v_add_co_u32_e32 v60, vcc, s6, v16
	s_movk_i32 s6, 0x6000
	s_nop 0
	v_addc_co_u32_e32 v61, vcc, 0, v17, vcc
	v_add_co_u32_e32 v68, vcc, s6, v16
	s_movk_i32 s6, 0x7000
	s_nop 0
	v_addc_co_u32_e32 v69, vcc, 0, v17, vcc
	v_add_co_u32_e32 v76, vcc, s6, v16
	s_lshl_b32 s6, s4, 1
	s_nop 0
	v_addc_co_u32_e32 v77, vcc, 0, v17, vcc
	s_waitcnt vmcnt(0)
	v_mov_b32_e32 v163, v162
	s_waitcnt lgkmcnt(0)
	v_pk_add_f32 v[0:1], v[24:25], v[26:27]
	v_pk_add_f32 v[2:3], v[28:29], v[30:31]
	v_pk_add_f32 v[4:5], v[32:33], v[34:35]
	v_pk_add_f32 v[6:7], v[36:37], v[38:39]
	v_pk_add_f32 v[0:1], v[0:1], v[2:3]
	v_pk_add_f32 v[2:3], v[4:5], v[6:7]
	v_mov_b32_e32 v165, v164
	v_pk_add_f32 v[0:1], v[0:1], v[2:3]
	v_mov_b32_e32 v167, v166
	v_pk_mul_f32 v[0:1], v[0:1], s[10:11] op_sel_hi:[1,0]
	s_and_b32 s10, s6, 0x300
	v_fma_f32 v1, -v0, v0, v1
	v_max_f32_e32 v1, 0, v1
	v_add_f32_e32 v1, 0x358637bd, v1
	v_rsq_f32_e32 v1, v1
	s_lshl_b32 s6, s4, 2
	s_and_b32 s86, s6, 0x600
	s_ashr_i32 s6, s5, 8
	ds_write_b64 v141, v[0:1] offset:10752
	global_load_dwordx4 v[0:3], v[16:17], off
	global_load_dwordx4 v[4:7], v[18:19], off
	global_load_dwordx4 v[8:11], v[20:21], off
	global_load_dwordx4 v[12:15], v[20:21], off offset:64
	s_nop 0
	global_load_dwordx4 v[16:19], v[22:23], off
	s_nop 0
	global_load_dwordx4 v[20:23], v[22:23], off offset:64
	s_nop 0
	global_load_dwordx4 v[24:27], v[52:53], off
	global_load_dwordx4 v[28:31], v[52:53], off offset:64
	global_load_dwordx4 v[32:35], v[68:69], off
	global_load_dwordx4 v[36:39], v[68:69], off offset:64
	global_load_dwordx4 v[40:43], v[76:77], off
	global_load_dwordx4 v[44:47], v[76:77], off offset:64
	global_load_dwordx4 v[48:51], v[60:61], off
	s_nop 0
	global_load_dwordx4 v[52:55], v[52:53], off offset:128
	s_nop 0
	global_load_dwordx4 v[56:59], v[60:61], off offset:64
	s_nop 0
	global_load_dwordx4 v[60:63], v[60:61], off offset:128
	s_nop 0
	global_load_dwordx4 v[64:67], v[68:69], off offset:128
	s_nop 0
	global_load_dwordx4 v[68:71], v[68:69], off offset:192
	s_nop 0
	global_load_dwordx4 v[72:75], v[76:77], off offset:128
	s_nop 0
	global_load_dwordx4 v[76:79], v[76:77], off offset:192
	s_mul_hi_i32 s11, s6, 0x1400000
	s_mul_i32 s12, s6, 0x1400000
	s_mul_hi_i32 s13, s6, 0x1c00000
	s_mul_i32 s6, s6, 0x1c00000
	s_add_u32 s1, s6, s8
	s_addc_u32 s9, s13, s9
	s_or_b32 s8, s1, s10
	s_mul_hi_i32 s1, s0, 0x60000
	s_mul_i32 s0, s0, 0x60000
	s_waitcnt lgkmcnt(0)
	s_add_u32 s0, s12, s0
	s_addc_u32 s1, s11, s1
	s_or_b32 s0, s0, s10
	v_lshl_add_u64 v[178:179], v[160:161], 0, s[86:87]
	v_mov_b32_e32 v169, v168
	v_mov_b32_e32 v171, v170
	v_mov_b32_e32 v173, v172
	v_mov_b32_e32 v175, v174
	v_mov_b32_e32 v177, v176
	v_lshl_add_u64 v[180:181], v[146:147], 0, s[8:9]
	v_lshl_add_u64 v[182:183], v[148:149], 0, s[8:9]
	v_lshl_add_u64 v[184:185], v[150:151], 0, s[8:9]
	v_lshl_add_u64 v[186:187], v[152:153], 0, s[0:1]
	v_lshl_add_u64 v[188:189], v[154:155], 0, s[0:1]
	v_lshl_add_u64 v[190:191], v[156:157], 0, s[0:1]
	v_lshl_add_u64 v[198:199], v[158:159], 0, s[0:1]
